# v54 + MLA tile loop as a two-barrier ping-pong: waves 4-7 run one barrier-step behind waves 0-3 (QK of one half beside softmax+PV of the other), tile t+1 staged during the odd step
# baseline (speedup 1.0000x reference)
; __global__ void __launch_bounds__(512, 2) fwd(Args args) {
;     ...
;         for (int item = F.vcu; item < 512; item += F.G) { const int bh = item >> 3, p = item & 7;
;             for (int h2 = 0; h2 < 2; ++h2) att::mla_unit(F, bh >> 4, bh & 15, h2 ? p : 15 - p); }
.LBB0_960:
	s_cmp_eq_u32 s99, 0
	s_cbranch_scc0 .Lpp_noextra
	s_barrier

; #define LAS __attribute__((address_space(3)))
; template <int MODE, int NQ> ...
;     ...
;     const LAS unsigned char* kb_l = lds + OFF_K + (lane & 31) * KP + hi * 16;
;     const LAS unsigned char* vb_l = lds + OFF_V + (4 * hi + ((lane & 15) >> 2)) * VP + (16 * ((lane >> 4) & 1) + 4 * (lane & 3)) * 2;
;     int j; unsigned long long rem = 0ull;
;     if (MODE == M_SEL) { rem = tmask; j = rem ? (int)__builtin_ctzll(rem) : -1; rem &= rem - 1ull; } else { j = jlo <= jhi ? jlo : -1; }
;     Stage st;
;     __syncthreads();
;     if (j >= 0) stage_load<HASP, HASV>(st, Kg + (size_t)j * 64 * ldk, ldk, Pg + (size_t)j * 64 * 64, Vg + (size_t)j * 64 * ldv, ldv, tid);
; __device__ __forceinline__ void mla_unit(Frame& F, int b, int hd, int qb) {
;     ...
;     const int lane = tid & 63, w = __builtin_amdgcn_readfirstlane(tid >> 6), ql = lane & 31, hi = lane >> 5;
;     const int ts = 256 * qb + 32 * w + ql; const size_t trow = (size_t)b * S + ts;
;     const float C = 0.07216878364870322f * LOG2E;
;     bf16x8 qf[12];
;     { const bf16_t* qrow = (const bf16_t*)(ws + WS_QMLA) + trow * 3072 + hd * 192 + 8 * hi;
; #pragma unroll
;       for (int d = 0; d < 12; ++d) qf[d] = *(const bf16x8*)(qrow + 16 * d); }
;     const bf16_t* KN = (const bf16_t*)(ws + WS_KN) + (size_t)b * S * 2048 + hd * 128; const bf16_t* VM = (const bf16_t*)(ws + WS_VM) + (size_t)b * S * 2048 + hd * 128;
;     const bf16_t* KPE = (const bf16_t*)(ws + WS_KPE) + (size_t)b * S * 64;
;     f32x16 O[4]; float m = -1e30f, l = 0.f; zero_o(O);
.LBB0_961:
	s_xor_b64 s[92:93], s[0:1], -1
	s_and_b64 s[0:1], s[0:1], exec
	v_mov_b32_e32 v16, v0
	s_cselect_b32 s2, s94, s81
	v_readfirstlane_b32 s0, v16
	s_ashr_i32 s0, s0, 1
	s_lshl_b32 s97, s2, 8
	s_andn2_b32 s0, s0, 31
	v_and_b32_e32 v4, 31, v16
	s_add_i32 s3, s0, s97
	v_or_b32_e32 v170, s3, v4
	v_ashrrev_i32_e32 v171, 31, v170
	v_lshl_add_u64 v[172:173], s[72:73], 0, v[170:171]
	v_bfe_u32 v17, v16, 5, 1
	v_mad_u64_u32 v[2:3], s[0:1], v172, s75, v[168:169]
	v_mad_i32_i24 v3, v173, s75, v3
	v_lshlrev_b32_e32 v166, 4, v17
	v_lshl_add_u64 v[2:3], v[2:3], 0, v[166:167]
	global_load_dwordx4 v[98:101], v[2:3], off
	global_load_dwordx4 v[102:105], v[2:3], off offset:32
	global_load_dwordx4 v[106:109], v[2:3], off offset:64
	global_load_dwordx4 v[110:113], v[2:3], off offset:96
	global_load_dwordx4 v[114:117], v[2:3], off offset:128
	global_load_dwordx4 v[118:121], v[2:3], off offset:160
	global_load_dwordx4 v[122:125], v[2:3], off offset:192
	global_load_dwordx4 v[126:129], v[2:3], off offset:224
	global_load_dwordx4 v[130:133], v[2:3], off offset:256
	global_load_dwordx4 v[134:137], v[2:3], off offset:288
	global_load_dwordx4 v[138:141], v[2:3], off offset:320
	global_load_dwordx4 v[142:145], v[2:3], off offset:352
	v_mul_u32_u24_e32 v2, 0x190, v4
	v_add3_u32 v171, 0, v2, v166
	v_ashrrev_i32_e32 v2, 4, v16
	v_ashrrev_i32_e32 v3, 31, v2
	v_lshlrev_b64 v[4:5], 12, v[2:3]
	v_lshlrev_b32_e32 v3, 4, v16
	s_mov_b64 s[0:1], 0x20000
	v_lshl_add_u64 v[6:7], s[84:85], 0, v[4:5]
	v_and_b32_e32 v166, 0xf0, v3
	v_lshl_add_u64 v[8:9], v[4:5], 0, s[0:1]
	v_lshl_add_u64 v[6:7], v[6:7], 0, v[166:167]
	v_lshl_add_u64 v[10:11], s[84:85], 0, v[8:9]
	s_barrier
	v_lshl_add_u64 v[10:11], v[10:11], 0, v[166:167]
	global_load_dwordx4 v[146:149], v[6:7], off
	global_load_dwordx4 v[150:153], v[10:11], off
	v_ashrrev_i32_e32 v6, 3, v16
	v_ashrrev_i32_e32 v7, 31, v6
	v_lshlrev_b64 v[10:11], 7, v[6:7]
	v_lshl_add_u64 v[12:13], s[88:89], 0, v[10:11]
	v_and_b32_e32 v176, 0x70, v3
	v_mov_b32_e32 v177, v167
	v_lshl_add_u64 v[8:9], s[86:87], 0, v[8:9]
	v_lshl_add_u64 v[12:13], v[12:13], 0, v[176:177]
	v_lshl_add_u64 v[14:15], s[86:87], 0, v[4:5]
	v_lshl_add_u64 v[8:9], v[8:9], 0, v[166:167]
	v_lshl_add_u64 v[14:15], v[14:15], 0, v[166:167]
	global_load_dwordx4 v[154:157], v[12:13], off
	global_load_dwordx4 v[158:161], v[14:15], off
	global_load_dwordx4 v[162:165], v[8:9], off
	v_lshlrev_b32_e32 v174, 2, v17
	v_lshrrev_b32_e32 v3, 2, v16
	v_and_b32_e32 v7, 16, v16
	v_lshlrev_b32_e32 v8, 2, v16
	s_lshl_b32 s0, s2, 2
	v_and_or_b32 v3, v3, 3, v174
	v_and_or_b32 v7, v8, 12, v7
	s_or_b32 s95, s0, 3
	v_mul_u32_u24_e32 v3, 0x140, v3
	v_lshlrev_b32_e32 v7, 1, v7
	v_mul_lo_u32 v183, v6, s76
	s_movk_i32 s0, 0x140
	v_and_b32_e32 v6, 7, v16
	v_add3_u32 v175, 0, v3, v7
	v_mul_lo_u32 v177, v2, s76
	v_mul_lo_u32 v184, v2, s0
	v_lshl_add_u64 v[2:3], s[90:91], 0, v[10:11]
	v_lshlrev_b32_e32 v6, 4, v6
	v_mov_b32_e32 v7, v167
	v_lshl_add_u64 v[178:179], v[2:3], 0, v[6:7]
	v_lshl_add_u64 v[2:3], s[82:83], 0, v[4:5]
	v_and_b32_e32 v4, 15, v16
	v_lshlrev_b32_e32 v4, 4, v4
	v_mov_b32_e32 v5, v167
	v_mov_b32_e32 v16, v167
	v_mov_b32_e32 v17, v167
	v_lshl_add_u64 v[180:181], v[2:3], 0, v[4:5]
	v_mov_b32_e32 v2, v167
	v_mov_b32_e32 v3, v167
	v_mov_b32_e32 v4, v167
	v_mov_b32_e32 v6, v167
	v_mov_b32_e32 v8, v167
	v_mov_b32_e32 v9, v167
	v_mov_b32_e32 v10, v167
	v_mov_b32_e32 v11, v167
	v_mov_b32_e32 v12, v167
	v_mov_b32_e32 v13, v167
	v_mov_b32_e32 v14, v167
	v_mov_b32_e32 v15, v167
	v_mov_b64_e32 v[32:33], v[16:17]
	v_mov_b64_e32 v[48:49], v[16:17]
	v_mov_b64_e32 v[64:65], v[16:17]
	s_or_b32 s96, s3, 31
	v_add_u32_e32 v182, 0x3200, v177
	v_add_u32_e32 v185, 0x2800, v184
	s_addk_i32 s97, 0x100
	v_sub_u32_e32 v187, v170, v174
	s_mov_b32 s33, 0
	v_mov_b32_e32 v188, 0
	v_mov_b32_e32 v190, 0xf149f2ca
	v_mov_b64_e32 v[30:31], v[14:15]
	v_mov_b64_e32 v[28:29], v[12:13]
	v_mov_b64_e32 v[26:27], v[10:11]
	v_mov_b64_e32 v[24:25], v[8:9]
	v_mov_b64_e32 v[22:23], v[6:7]
	v_mov_b64_e32 v[20:21], v[4:5]
	v_mov_b64_e32 v[18:19], v[2:3]
	v_mov_b64_e32 v[46:47], v[14:15]
	v_mov_b64_e32 v[44:45], v[12:13]
	v_mov_b64_e32 v[42:43], v[10:11]
	v_mov_b64_e32 v[40:41], v[8:9]
	v_mov_b64_e32 v[38:39], v[6:7]
	v_mov_b64_e32 v[36:37], v[4:5]
	v_mov_b64_e32 v[34:35], v[2:3]
	v_mov_b64_e32 v[62:63], v[14:15]
	v_mov_b64_e32 v[60:61], v[12:13]
	v_mov_b64_e32 v[58:59], v[10:11]
	v_mov_b64_e32 v[56:57], v[8:9]
	v_mov_b64_e32 v[54:55], v[6:7]
	v_mov_b64_e32 v[52:53], v[4:5]
	v_mov_b64_e32 v[50:51], v[2:3]
	s_mov_b32 s64, 0
	v_readfirstlane_b32 s99, v0
	s_lshr_b32 s99, s99, 8
	v_add_u32_e32 v254, v177, v166
	s_waitcnt vmcnt(4)
	ds_write_b128 v254, v[146:149]
	v_add_u32_e32 v254, v182, v166
	s_waitcnt vmcnt(3)
	ds_write_b128 v254, v[150:153]
	v_add_u32_e32 v254, v183, v176
	s_waitcnt vmcnt(2)
	ds_write_b128 v254, v[154:157] offset:256
	v_add_u32_e32 v254, v184, v166
	s_waitcnt vmcnt(1)
	ds_write_b128 v254, v[158:161] offset:51200
	v_add_u32_e32 v254, v185, v166
	s_waitcnt vmcnt(0)
	ds_write_b128 v254, v[162:165] offset:51200
	s_waitcnt lgkmcnt(0)
	v_lshl_add_u64 v[246:247], s[30:31], 0, v[180:181]
	v_add_co_u32_e32 v248, vcc, 0x34840000, v246
	s_nop 1
	v_addc_co_u32_e32 v249, vcc, 0, v247, vcc
	v_add_co_u32_e32 v250, vcc, 0x34860000, v246
	s_nop 1
	v_addc_co_u32_e32 v251, vcc, 0, v247, vcc
	global_load_dwordx4 v[146:149], v[248:249], off
	global_load_dwordx4 v[150:153], v[250:251], off
	v_add_co_u32_e32 v250, vcc, 0x38840000, v246
	v_lshl_add_u64 v[248:249], s[30:31], 0, v[178:179]
	s_nop 0
	v_addc_co_u32_e32 v251, vcc, 0, v247, vcc
	v_add_co_u32_e32 v246, vcc, 0x38860000, v246
	global_load_dwordx4 v[154:157], v[248:249], off
	global_load_dwordx4 v[158:161], v[250:251], off
	s_nop 0
	v_addc_co_u32_e32 v247, vcc, 0, v247, vcc
	global_load_dwordx4 v[162:165], v[246:247], off
	s_mov_b64 s[0:1], 0x2000
	v_lshl_add_u64 v[178:179], v[178:179], 0, s[0:1]
	s_mov_b64 s[0:1], 0x40000
	v_lshl_add_u64 v[180:181], v[180:181], 0, s[0:1]
	s_cmp_eq_u32 s99, 0
	s_cbranch_scc1 .LBB0_962
	s_barrier
; #define LAS __attribute__((address_space(3)))
; template <int MODE, int NQ> ...
;     ...
;     while (j >= 0) {
;         const int bsel = it & 1;
;         stage_store<HASP, HASV>(st, lds + OFF_K + bsel * KBUF, lds + OFF_V + bsel * VBUF, tid);
;         __syncthreads();
;         int jn;
;         if (MODE == M_SEL) { jn = rem ? (int)__builtin_ctzll(rem) : -1; rem &= rem - 1ull; } else { jn = (j + 1 <= jhi) ? j + 1 : -1; }
;         if (jn >= 0) stage_load<HASP, HASV>(st, Kg + (size_t)jn * 64 * ldk, ldk, Pg + (size_t)jn * 64 * 64, Vg + (size_t)jn * 64 * ldv, ldv, tid);
;         const bool lvw = (MODE == M_SEL) ? (((mymask >> j) & 1ull) != 0ull) : true;
;         if (!((MODE == M_MLA && 64 * j > wmax) || (MODE == M_SEL && !__any(lvw)))) {
;             const LAS unsigned char* kb = kb_l + bsel * KBUF; const LAS unsigned char* vb = vb_l + bsel * VBUF;
;             f32x16 s0, s1;
; #pragma unroll
;             for (int r = 0; r < 16; ++r) { s0[r] = 0.f; s1[r] = 0.f; }
;             {
;                 constexpr int KW = (NQ == 8) ? 6 : ATT_KW12;
;                 bf16x8 kf[KW];
; #pragma unroll
;                 for (int i = 0; i < KW; ++i) kf[i] = *(const LAS bf16x8*)(kb + (i & 1) * 32 * KP + (i >> 1) * 32);
;                 __builtin_amdgcn_sched_barrier(0);
; #pragma unroll
;                 for (int i = 0; i < 2 * NQ; ++i) {
;                     if (i & 1) s1 = __builtin_amdgcn_mfma_f32_32x32x16_bf16(kf[i % KW], qf[i >> 1], s1, 0, 0, 0);
;                     else s0 = __builtin_amdgcn_mfma_f32_32x32x16_bf16(kf[i % KW], qf[i >> 1], s0, 0, 0, 0);
;                     if (i + KW < 2 * NQ) { kf[i % KW] = *(const LAS bf16x8*)(kb + ((i + KW) & 1) * 32 * KP + ((i + KW) >> 1) * 32); __builtin_amdgcn_sched_barrier(0); }
;                 }
;             }
.LBB0_962:
	s_and_b32 s65, s64, 1
	s_mul_i32 s0, s65, 0x6400
	s_waitcnt lgkmcnt(0)
	s_barrier
	s_cmp_eq_u32 s99, 0
	s_cbranch_scc1 .LBB0_964
	s_cmp_ge_u32 s64, s95
	s_cbranch_scc1 .Lpp_stB_done
	s_xor_b32 s1, s65, 1
	s_mul_i32 s2, s1, 0x5000
	s_mul_i32 s1, s1, 0x6400
	v_add3_u32 v254, s1, v177, v166
	s_waitcnt vmcnt(4)
	ds_write_b128 v254, v[146:149]
	v_add3_u32 v254, s1, v182, v166
	s_waitcnt vmcnt(3)
	ds_write_b128 v254, v[150:153]
	v_add3_u32 v254, s1, v183, v176
	s_waitcnt vmcnt(2)
	ds_write_b128 v254, v[154:157] offset:256
	v_add3_u32 v254, s2, v184, v166
	s_waitcnt vmcnt(1)
	ds_write_b128 v254, v[158:161] offset:51200
	v_add3_u32 v254, s2, v185, v166
	s_waitcnt vmcnt(0)
	ds_write_b128 v254, v[162:165] offset:51200
	s_add_i32 s1, s64, 1
	s_cmp_ge_u32 s1, s95
	s_cbranch_scc1 .Lpp_stB_done
	s_waitcnt lgkmcnt(0)
	v_lshl_add_u64 v[246:247], s[30:31], 0, v[180:181]
	v_add_co_u32_e32 v248, vcc, 0x34840000, v246
	s_nop 1
	v_addc_co_u32_e32 v249, vcc, 0, v247, vcc
	v_add_co_u32_e32 v250, vcc, 0x34860000, v246
	s_nop 1
	v_addc_co_u32_e32 v251, vcc, 0, v247, vcc
	global_load_dwordx4 v[146:149], v[248:249], off
	global_load_dwordx4 v[150:153], v[250:251], off
	v_add_co_u32_e32 v250, vcc, 0x38840000, v246
	v_lshl_add_u64 v[248:249], s[30:31], 0, v[178:179]
	s_nop 0
	v_addc_co_u32_e32 v251, vcc, 0, v247, vcc
	v_add_co_u32_e32 v246, vcc, 0x38860000, v246
	global_load_dwordx4 v[154:157], v[248:249], off
	global_load_dwordx4 v[158:161], v[250:251], off
	s_nop 0
	v_addc_co_u32_e32 v247, vcc, 0, v247, vcc
	global_load_dwordx4 v[162:165], v[246:247], off
.Lpp_stB_done:
.LBB0_964:
	s_cmp_gt_i32 s33, s96
	s_cbranch_scc1 .Lpp_mid_skip
	v_add_u32_e32 v189, s0, v171
	ds_read_b128 v[66:69], v189
	ds_read_b128 v[192:195], v189 offset:32
	ds_read_b128 v[82:85], v189 offset:12800
	ds_read_b128 v[196:199], v189 offset:12832
	ds_read_b128 v[200:203], v189 offset:64
	ds_read_b128 v[204:207], v189 offset:96
	ds_read_b128 v[208:211], v189 offset:12864
	ds_read_b128 v[212:215], v189 offset:12896
	ds_read_b128 v[216:219], v189 offset:128
	ds_read_b128 v[220:223], v189 offset:160
	ds_read_b128 v[224:227], v189 offset:12928
	ds_read_b128 v[228:231], v189 offset:12960
	s_waitcnt lgkmcnt(11)
	v_mfma_f32_32x32x16_bf16 v[66:81], v[66:69], v[98:101], 0
	ds_read_b128 v[232:235], v189 offset:192
	s_waitcnt lgkmcnt(10)
	v_mfma_f32_32x32x16_bf16 v[82:97], v[82:85], v[98:101], 0
	ds_read_b128 v[236:239], v189 offset:12992
	v_mfma_f32_32x32x16_bf16 v[66:81], v[192:195], v[102:105], v[66:81]
	ds_read_b128 v[240:243], v189 offset:224
	s_waitcnt lgkmcnt(11)
	v_mfma_f32_32x32x16_bf16 v[82:97], v[196:199], v[102:105], v[82:97]
	ds_read_b128 v[192:195], v189 offset:13024
	s_waitcnt lgkmcnt(11)
	v_mfma_f32_32x32x16_bf16 v[66:81], v[200:203], v[106:109], v[66:81]
	ds_read_b128 v[196:199], v189 offset:256
	s_waitcnt lgkmcnt(10)
	v_mfma_f32_32x32x16_bf16 v[82:97], v[208:211], v[106:109], v[82:97]
	ds_read_b128 v[200:203], v189 offset:13056
	v_mfma_f32_32x32x16_bf16 v[66:81], v[204:207], v[110:113], v[66:81]
	ds_read_b128 v[208:211], v189 offset:288
	s_waitcnt lgkmcnt(11)
	v_mfma_f32_32x32x16_bf16 v[82:97], v[212:215], v[110:113], v[82:97]
	ds_read_b128 v[204:207], v189 offset:13088
	s_waitcnt lgkmcnt(11)
	v_mfma_f32_32x32x16_bf16 v[66:81], v[216:219], v[114:117], v[66:81]
	ds_read_b128 v[212:215], v189 offset:320
	s_waitcnt lgkmcnt(10)
	v_mfma_f32_32x32x16_bf16 v[82:97], v[224:227], v[114:117], v[82:97]
	ds_read_b128 v[216:219], v189 offset:13120
	v_mfma_f32_32x32x16_bf16 v[66:81], v[220:223], v[118:121], v[66:81]
	ds_read_b128 v[224:227], v189 offset:352
	s_waitcnt lgkmcnt(11)
	v_mfma_f32_32x32x16_bf16 v[82:97], v[228:231], v[118:121], v[82:97]
	ds_read_b128 v[220:223], v189 offset:13152
	s_waitcnt lgkmcnt(11)
	v_mfma_f32_32x32x16_bf16 v[66:81], v[232:235], v[122:125], v[66:81]
	v_cmp_gt_i32_e32 vcc, 63, v187
	s_waitcnt lgkmcnt(10)
	v_mfma_f32_32x32x16_bf16 v[82:97], v[236:239], v[122:125], v[82:97]
	s_waitcnt lgkmcnt(9)
	v_mfma_f32_32x32x16_bf16 v[66:81], v[240:243], v[126:129], v[66:81]
	s_waitcnt lgkmcnt(8)
	v_mfma_f32_32x32x16_bf16 v[82:97], v[192:195], v[126:129], v[82:97]
	s_waitcnt lgkmcnt(7)
	v_mfma_f32_32x32x16_bf16 v[66:81], v[196:199], v[130:133], v[66:81]
	s_waitcnt lgkmcnt(6)
	v_mfma_f32_32x32x16_bf16 v[82:97], v[200:203], v[130:133], v[82:97]
	s_waitcnt lgkmcnt(5)
	v_mfma_f32_32x32x16_bf16 v[66:81], v[208:211], v[134:137], v[66:81]
	s_waitcnt lgkmcnt(4)
	v_mfma_f32_32x32x16_bf16 v[82:97], v[204:207], v[134:137], v[82:97]
	s_waitcnt lgkmcnt(3)
	v_mfma_f32_32x32x16_bf16 v[66:81], v[212:215], v[138:141], v[66:81]
	s_waitcnt lgkmcnt(2)
	v_mfma_f32_32x32x16_bf16 v[82:97], v[216:219], v[138:141], v[82:97]
	s_waitcnt lgkmcnt(1)
	v_mfma_f32_32x32x16_bf16 v[66:81], v[224:227], v[142:145], v[66:81]
	s_waitcnt lgkmcnt(0)
	v_mfma_f32_32x32x16_bf16 v[82:97], v[220:223], v[142:145], v[82:97]
	s_cbranch_vccz .LBB0_967
; template <int MODE, int NQ> ...
;     ...
;         stage_store<HASP, HASV>(st, lds + OFF_K + bsel * KBUF, lds + OFF_V + bsel * VBUF, tid);
;         __syncthreads();
;         int jn;
;         if (MODE == M_SEL) { jn = rem ? (int)__builtin_ctzll(rem) : -1; rem &= rem - 1ull; } else { jn = (j + 1 <= jhi) ? j + 1 : -1; }
;         if (jn >= 0) stage_load<HASP, HASV>(st, Kg + (size_t)jn * 64 * ldk, ldk, Pg + (size_t)jn * 64 * 64, Vg + (size_t)jn * 64 * ldv, ldv, tid);
;     ...
;             if (MODE == M_WIN || MODE == M_MLA || MODE == M_SEL) need = __any(!((hl >= 63) && (ll < 0)));
;             if (need) {
;                 const float NEG = -__builtin_inff();
; #pragma unroll
;                 for (int r = 0; r < 16; ++r) { const int c = (r & 3) + 8 * (r >> 2);
;                     if (!(lv && c <= hl && c > ll)) s0[r] = NEG;
;                     if (!(lv && c + 32 <= hl && c + 32 > ll)) s1[r] = NEG; }
;             }
	v_cmp_gt_i32_e64 s[60:61], 26, v187
	v_cmp_gt_i32_e64 s[62:63], 27, v187
	v_cmp_gt_i32_e64 s[58:59], 25, v187
	s_and_b64 s[60:61], s[62:63], s[60:61]
	v_cmp_gt_i32_e64 s[56:57], 24, v187
	s_and_b64 s[58:59], s[60:61], s[58:59]
	v_cmp_gt_i32_e64 s[54:55], 19, v187
	s_and_b64 s[56:57], s[58:59], s[56:57]
	v_cmp_gt_i32_e64 s[52:53], 18, v187
	s_and_b64 s[54:55], s[56:57], s[54:55]
	v_cmp_gt_i32_e64 s[50:51], 17, v187
	s_and_b64 s[52:53], s[54:55], s[52:53]
	v_cmp_gt_i32_e64 s[48:49], 16, v187
	s_and_b64 s[50:51], s[52:53], s[50:51]
	v_cmp_gt_i32_e64 s[46:47], 11, v187
	s_and_b64 s[48:49], s[50:51], s[48:49]
	v_cmp_gt_i32_e64 s[44:45], 10, v187
	s_and_b64 s[46:47], s[48:49], s[46:47]
	v_cmp_gt_i32_e64 s[42:43], 9, v187
	s_and_b64 s[44:45], s[46:47], s[44:45]
	v_cmp_gt_i32_e64 s[40:41], 8, v187
	s_and_b64 s[42:43], s[44:45], s[42:43]
	v_cmp_gt_i32_e64 s[38:39], 3, v187
	s_and_b64 s[40:41], s[42:43], s[40:41]
	v_cmp_gt_i32_e64 s[36:37], 2, v187
	s_and_b64 s[38:39], s[40:41], s[38:39]
	v_cmp_gt_i32_e64 s[34:35], 1, v187
	s_and_b64 s[36:37], s[38:39], s[36:37]
	v_cmp_gt_i32_e64 s[28:29], 0, v187
	s_and_b64 s[34:35], s[36:37], s[34:35]
	s_and_b64 s[28:29], s[34:35], s[28:29]
	v_cmp_gt_i32_e64 s[26:27], 58, v187
	v_cndmask_b32_e64 v66, v66, v1, s[28:29]
	v_cmp_gt_i32_e64 s[28:29], 59, v187
	v_cmp_gt_i32_e64 s[24:25], 57, v187
	s_and_b64 s[26:27], s[28:29], s[26:27]
	v_cmp_gt_i32_e64 s[22:23], 56, v187
	s_and_b64 s[24:25], s[26:27], s[24:25]
	v_cmp_gt_i32_e64 s[20:21], 51, v187
	s_and_b64 s[22:23], s[24:25], s[22:23]
	v_cmp_gt_i32_e64 s[18:19], 50, v187
	s_and_b64 s[20:21], s[22:23], s[20:21]
	v_cmp_gt_i32_e64 s[0:1], 49, v187
	s_and_b64 s[18:19], s[20:21], s[18:19]
	v_cmp_gt_i32_e64 s[16:17], 48, v187
	s_and_b64 s[0:1], s[18:19], s[0:1]
	v_cmp_gt_i32_e64 s[14:15], 43, v187
	v_cndmask_b32_e64 v91, v91, v1, s[0:1]
	s_and_b64 s[0:1], s[0:1], s[16:17]
	v_cmp_gt_i32_e64 s[12:13], 42, v187
	v_cndmask_b32_e64 v90, v90, v1, s[0:1]
	s_and_b64 s[0:1], s[0:1], s[14:15]
	v_cmp_gt_i32_e64 s[10:11], 41, v187
	v_cndmask_b32_e64 v89, v89, v1, s[0:1]
	s_and_b64 s[0:1], s[0:1], s[12:13]
	v_cmp_gt_i32_e64 s[8:9], 40, v187
	v_cndmask_b32_e64 v88, v88, v1, s[0:1]
	s_and_b64 s[0:1], s[0:1], s[10:11]
	v_cmp_gt_i32_e64 s[6:7], 35, v187
	v_cndmask_b32_e64 v87, v87, v1, s[0:1]
	s_and_b64 s[0:1], s[0:1], s[8:9]
	v_cmp_gt_i32_e64 s[4:5], 34, v187
	v_cndmask_b32_e64 v86, v86, v1, s[0:1]
	s_and_b64 s[0:1], s[0:1], s[6:7]
	v_cmp_gt_i32_e64 s[2:3], 33, v187
	v_cndmask_b32_e64 v85, v85, v1, s[0:1]
	s_and_b64 s[0:1], s[0:1], s[4:5]
	v_cmp_gt_i32_e32 vcc, 32, v187
	v_cndmask_b32_e64 v84, v84, v1, s[0:1]
	s_and_b64 s[0:1], s[0:1], s[2:3]
	s_and_b64 vcc, s[0:1], vcc
	v_cndmask_b32_e64 v81, v81, v1, s[62:63]
	v_cndmask_b32_e64 v80, v80, v1, s[60:61]
	v_cndmask_b32_e64 v79, v79, v1, s[58:59]
	v_cndmask_b32_e64 v78, v78, v1, s[56:57]
	v_cndmask_b32_e64 v77, v77, v1, s[54:55]
	v_cndmask_b32_e64 v76, v76, v1, s[52:53]
	v_cndmask_b32_e64 v75, v75, v1, s[50:51]
	v_cndmask_b32_e64 v74, v74, v1, s[48:49]
	v_cndmask_b32_e64 v73, v73, v1, s[46:47]
	v_cndmask_b32_e64 v72, v72, v1, s[44:45]
	v_cndmask_b32_e64 v71, v71, v1, s[42:43]
	v_cndmask_b32_e64 v70, v70, v1, s[40:41]
	v_cndmask_b32_e64 v69, v69, v1, s[38:39]
	v_cndmask_b32_e64 v68, v68, v1, s[36:37]
	v_cndmask_b32_e64 v67, v67, v1, s[34:35]
	v_cndmask_b32_e64 v97, v97, v1, s[28:29]
	v_cndmask_b32_e64 v96, v96, v1, s[26:27]
	v_cndmask_b32_e64 v95, v95, v1, s[24:25]
	v_cndmask_b32_e64 v94, v94, v1, s[22:23]
	v_cndmask_b32_e64 v93, v93, v1, s[20:21]
	v_cndmask_b32_e64 v92, v92, v1, s[18:19]
	v_cndmask_b32_e64 v83, v83, v1, s[0:1]
	v_cndmask_b32_e32 v82, v82, v1, vcc
.LBB0_967:
	s_waitcnt lgkmcnt(0)
	s_barrier
	s_cmp_eq_u32 s99, 0
	s_cbranch_scc0 .Lpp_midc_done
	s_cmp_ge_u32 s64, s95
	s_cbranch_scc1 .Lpp_stA1_done
	s_xor_b32 s1, s65, 1
	s_mul_i32 s2, s1, 0x5000
	s_mul_i32 s1, s1, 0x6400
	v_add3_u32 v254, s1, v177, v166
	s_waitcnt vmcnt(4)
	ds_write_b128 v254, v[146:149]
	v_add3_u32 v254, s1, v182, v166
	s_waitcnt vmcnt(3)
	ds_write_b128 v254, v[150:153]
	v_add3_u32 v254, s1, v183, v176
	s_waitcnt vmcnt(2)
	ds_write_b128 v254, v[154:157] offset:256
	v_add3_u32 v254, s2, v184, v166
	s_waitcnt vmcnt(1)
	ds_write_b128 v254, v[158:161] offset:51200
	v_add3_u32 v254, s2, v185, v166
	s_waitcnt vmcnt(0)
	ds_write_b128 v254, v[162:165] offset:51200
	s_add_i32 s1, s64, 1
	s_cmp_ge_u32 s1, s95
	s_cbranch_scc1 .Lpp_stA1_done
	s_waitcnt lgkmcnt(0)
	v_lshl_add_u64 v[246:247], s[30:31], 0, v[180:181]
	v_add_co_u32_e32 v248, vcc, 0x34840000, v246
	s_nop 1
	v_addc_co_u32_e32 v249, vcc, 0, v247, vcc
	v_add_co_u32_e32 v250, vcc, 0x34860000, v246
	s_nop 1
	v_addc_co_u32_e32 v251, vcc, 0, v247, vcc
	global_load_dwordx4 v[146:149], v[248:249], off
	global_load_dwordx4 v[150:153], v[250:251], off
	v_add_co_u32_e32 v250, vcc, 0x38840000, v246
	v_lshl_add_u64 v[248:249], s[30:31], 0, v[178:179]
	s_nop 0
	v_addc_co_u32_e32 v251, vcc, 0, v247, vcc
	v_add_co_u32_e32 v246, vcc, 0x38860000, v246
	global_load_dwordx4 v[154:157], v[248:249], off
	global_load_dwordx4 v[158:161], v[250:251], off
	s_nop 0
	v_addc_co_u32_e32 v247, vcc, 0, v247, vcc
	global_load_dwordx4 v[162:165], v[246:247], off
; __device__ __forceinline__ float xhalf_max(float x) { const auto r = __builtin_amdgcn_permlane32_swap(__float_as_uint(x), __float_as_uint(x), false, false); return fmaxf(__uint_as_float(r[0]), __uint_as_float(r[1])); }
; __device__ __forceinline__ float xhalf_sum(float x) { const auto r = __builtin_amdgcn_permlane32_swap(__float_as_uint(x), __float_as_uint(x), false, false); return __uint_as_float(r[0]) + __uint_as_float(r[1]); }
; template <int MODE, int NQ> ...
;     ...
;                 float mx = s0[0];
; #pragma unroll
;                 for (int r = 1; r < 16; ++r) mx = fmaxf(mx, s0[r]);
; #pragma unroll
;                 for (int r = 0; r < 16; ++r) mx = fmaxf(mx, s1[r]);
;                 mx = xhalf_max(mx);
;                 if (MODE == M_SEL) mx = lv ? mx : -__builtin_inff();
;                 const float mn = fmaxf(m, mx * C), alpha = __builtin_amdgcn_exp2f(m - mn);
;                 m = mn;
;                 float rs = 0.f;
; #pragma unroll
;                 for (int r = 0; r < 16; ++r) { s0[r] = __builtin_amdgcn_exp2f(s0[r] * C - mn); s1[r] = __builtin_amdgcn_exp2f(s1[r] * C - mn); rs += s0[r] + s1[r]; }
;                 rs = xhalf_sum(rs);
;                 if (MODE == M_SEL) rs = lv ? rs : 0.f;
;                 l = l * alpha + rs;
;                 if (MODE != M_CMP1) {
;                     if (!__all(alpha == 1.0f)) {
; #pragma unroll
;                         for (int db = 0; db < 4; ++db)
; #pragma unroll
;                             for (int r = 0; r < 16; ++r) O[db][r] *= alpha;
;                     }
;                 }
.Lpp_stA1_done:
.Lpp_midc_done:
	s_nop 8
	v_max_f32_e32 v189, v67, v67
	v_max_f32_e32 v191, v66, v66
	v_max_f32_e32 v189, v191, v189
	v_max3_f32 v189, v189, v68, v69
	v_max3_f32 v189, v189, v70, v71
	v_max3_f32 v189, v189, v72, v73
	v_max3_f32 v189, v189, v74, v75
	v_max3_f32 v189, v189, v76, v77
	v_max3_f32 v189, v189, v78, v79
	v_max3_f32 v189, v189, v80, v81
	v_max3_f32 v189, v189, v82, v83
	v_max3_f32 v189, v189, v84, v85
	v_max3_f32 v189, v189, v86, v87
	v_max3_f32 v189, v189, v88, v89
	v_max3_f32 v189, v189, v90, v91
	v_max3_f32 v189, v189, v92, v93
	v_max3_f32 v189, v189, v94, v95
	v_max3_f32 v189, v189, v96, v97
	v_mov_b32_e32 v191, v189
	s_nop 1
	v_permlane32_swap_b32_e32 v189, v191
	v_max_f32_e32 v191, v191, v191
	v_max_f32_e32 v189, v189, v189
	v_max_f32_e32 v189, v189, v191
	v_mul_f32_e32 v189, 0x3dd53b94, v189
	v_max_f32_e32 v191, v190, v190
	v_max_f32_e32 v189, v191, v189
	v_fma_f32 v66, v66, s77, -v189
	v_exp_f32_e32 v191, v66
	v_fma_f32 v66, v82, s77, -v189
	v_exp_f32_e32 v82, v66
	v_fma_f32 v66, v67, s77, -v189
	v_exp_f32_e32 v193, v66
	v_fma_f32 v66, v83, s77, -v189
	v_fma_f32 v68, v68, s77, -v189
	v_exp_f32_e32 v67, v66
	v_exp_f32_e32 v195, v68
	v_fma_f32 v68, v84, s77, -v189
	v_exp_f32_e32 v68, v68
	v_fma_f32 v69, v69, s77, -v189
	v_add_f32_e32 v83, v191, v82
	v_exp_f32_e32 v197, v69
	v_fma_f32 v69, v85, s77, -v189
	v_sub_f32_e32 v66, v190, v189
	v_add_f32_e32 v190, 0, v83
	v_exp_f32_e32 v83, v69
	v_add_f32_e32 v192, v193, v67
	v_fma_f32 v70, v70, s77, -v189
	v_add_f32_e32 v69, v192, v190
	v_add_f32_e32 v84, v195, v68
	v_exp_f32_e32 v190, v70
	v_fma_f32 v70, v86, s77, -v189
	v_add_f32_e32 v69, v84, v69
	v_exp_f32_e32 v84, v70
	v_fma_f32 v70, v71, s77, -v189
	v_add_f32_e32 v194, v197, v83
	v_exp_f32_e32 v192, v70
	v_fma_f32 v70, v87, s77, -v189
	v_fma_f32 v71, v72, s77, -v189
	v_exp_f32_e32 v85, v70
	v_add_f32_e32 v69, v194, v69
	v_exp_f32_e32 v194, v71
	v_fma_f32 v71, v88, s77, -v189
	v_exp_f32_e32 v72, v71
	v_add_f32_e32 v70, v190, v84
	v_add_f32_e32 v69, v70, v69
	v_add_f32_e32 v70, v192, v85
	v_fma_f32 v71, v73, s77, -v189
	v_exp_f32_e32 v196, v71
	v_fma_f32 v71, v89, s77, -v189
	v_add_f32_e32 v69, v70, v69
	v_add_f32_e32 v70, v194, v72
	v_exp_f32_e32 v86, v71
	v_add_f32_e32 v71, v70, v69
	v_fma_f32 v69, v74, s77, -v189
	v_exp_f32_e32 v87, v69
	v_fma_f32 v69, v90, s77, -v189
	v_exp_f32_e32 v69, v69
	v_add_f32_e32 v73, v196, v86
	v_fma_f32 v70, v75, s77, -v189
	v_add_f32_e32 v71, v73, v71
	v_add_f32_e32 v73, v87, v69
	v_exp_f32_e32 v88, v70
	v_fma_f32 v70, v91, s77, -v189
	v_add_f32_e32 v73, v73, v71
	v_fma_f32 v71, v76, s77, -v189
	v_exp_f32_e32 v70, v70
	v_exp_f32_e32 v89, v71
	v_fma_f32 v71, v92, s77, -v189
	v_fma_f32 v75, v77, s77, -v189
	v_exp_f32_e32 v71, v71
	v_exp_f32_e32 v90, v75
	v_fma_f32 v75, v93, s77, -v189
	v_fma_f32 v76, v78, s77, -v189
	v_exp_f32_e32 v75, v75
	v_exp_f32_e32 v91, v76
	v_fma_f32 v76, v94, s77, -v189
	v_fma_f32 v77, v79, s77, -v189
	v_exp_f32_e32 v76, v76
	v_exp_f32_e32 v92, v77
	v_fma_f32 v77, v95, s77, -v189
	v_add_f32_e32 v74, v88, v70
	v_exp_f32_e32 v78, v77
	v_add_f32_e32 v73, v74, v73
	v_add_f32_e32 v74, v89, v71
	v_add_f32_e32 v73, v74, v73
	v_add_f32_e32 v74, v90, v75
	v_add_f32_e32 v73, v74, v73
	v_add_f32_e32 v74, v91, v76
	v_add_f32_e32 v73, v74, v73
	v_add_f32_e32 v74, v92, v78
	v_add_f32_e32 v73, v74, v73
	v_fma_f32 v74, v80, s77, -v189
	v_exp_f32_e32 v80, v74
	v_fma_f32 v74, v96, s77, -v189
	v_exp_f32_e32 v77, v74
	v_fma_f32 v74, v81, s77, -v189
	v_exp_f32_e32 v81, v74
	v_fma_f32 v74, v97, s77, -v189
	v_exp_f32_e32 v79, v74
	v_exp_f32_e32 v66, v66
	v_add_f32_e32 v74, v80, v77
	v_add_f32_e32 v73, v74, v73
	v_add_f32_e32 v74, v81, v79
	v_add_f32_e32 v73, v74, v73
	v_mov_b32_e32 v74, v73
	v_cmp_eq_f32_e32 vcc, 1.0, v66
	s_cmp_eq_u64 vcc, exec
	v_permlane32_swap_b32_e32 v73, v74
	s_cbranch_scc1 .LBB0_969
	v_pk_mul_f32 v[64:65], v[64:65], v[66:67] op_sel_hi:[1,0]
	v_pk_mul_f32 v[62:63], v[62:63], v[66:67] op_sel_hi:[1,0]
	v_pk_mul_f32 v[60:61], v[60:61], v[66:67] op_sel_hi:[1,0]
	v_pk_mul_f32 v[58:59], v[58:59], v[66:67] op_sel_hi:[1,0]
	v_pk_mul_f32 v[56:57], v[56:57], v[66:67] op_sel_hi:[1,0]
	v_pk_mul_f32 v[54:55], v[54:55], v[66:67] op_sel_hi:[1,0]
	v_pk_mul_f32 v[52:53], v[52:53], v[66:67] op_sel_hi:[1,0]
	v_pk_mul_f32 v[50:51], v[50:51], v[66:67] op_sel_hi:[1,0]
	v_pk_mul_f32 v[48:49], v[48:49], v[66:67] op_sel_hi:[1,0]
	v_pk_mul_f32 v[46:47], v[46:47], v[66:67] op_sel_hi:[1,0]
	v_pk_mul_f32 v[44:45], v[44:45], v[66:67] op_sel_hi:[1,0]
	v_pk_mul_f32 v[42:43], v[42:43], v[66:67] op_sel_hi:[1,0]
	v_pk_mul_f32 v[40:41], v[40:41], v[66:67] op_sel_hi:[1,0]
	v_pk_mul_f32 v[38:39], v[38:39], v[66:67] op_sel_hi:[1,0]
	v_pk_mul_f32 v[36:37], v[36:37], v[66:67] op_sel_hi:[1,0]
	v_pk_mul_f32 v[34:35], v[34:35], v[66:67] op_sel_hi:[1,0]
	v_pk_mul_f32 v[32:33], v[32:33], v[66:67] op_sel_hi:[1,0]
	v_pk_mul_f32 v[30:31], v[30:31], v[66:67] op_sel_hi:[1,0]
	v_pk_mul_f32 v[28:29], v[28:29], v[66:67] op_sel_hi:[1,0]
	v_pk_mul_f32 v[26:27], v[26:27], v[66:67] op_sel_hi:[1,0]
	v_pk_mul_f32 v[24:25], v[24:25], v[66:67] op_sel_hi:[1,0]
	v_pk_mul_f32 v[22:23], v[22:23], v[66:67] op_sel_hi:[1,0]
	v_pk_mul_f32 v[20:21], v[20:21], v[66:67] op_sel_hi:[1,0]
	v_pk_mul_f32 v[18:19], v[18:19], v[66:67] op_sel_hi:[1,0]
	v_pk_mul_f32 v[16:17], v[16:17], v[66:67] op_sel_hi:[1,0]
	v_pk_mul_f32 v[14:15], v[14:15], v[66:67] op_sel_hi:[1,0]
	v_pk_mul_f32 v[12:13], v[12:13], v[66:67] op_sel_hi:[1,0]
	v_pk_mul_f32 v[10:11], v[10:11], v[66:67] op_sel_hi:[1,0]
	v_pk_mul_f32 v[8:9], v[8:9], v[66:67] op_sel_hi:[1,0]
	v_pk_mul_f32 v[6:7], v[6:7], v[66:67] op_sel_hi:[1,0]
	v_pk_mul_f32 v[4:5], v[4:5], v[66:67] op_sel_hi:[1,0]
	v_pk_mul_f32 v[2:3], v[2:3], v[66:67] op_sel_hi:[1,0]

; template <int MODE, int NQ> ...
;     ...
;         j = jn; ++it;
.Lpp_stA2_done:
.LBB0_970:
.Lst_mla_skip:
	v_mov_b32_e32 v189, v190
